# P1 weight-row quantisation loop: the wave's later rows prefetched to L2 by scratch loads before the loop (software prefetch)
# speedup vs baseline: 1.0012x; 1.0012x over previous
; #define GAS __attribute__((address_space(1)))
; __device__ __forceinline__ int lane_now() { int l; asm volatile("v_mbcnt_lo_u32_b32 %0, -1, 0\n\tv_mbcnt_hi_u32_b32 %0, -1, %0" : "=v"(l)); return l; }
; __device__ __forceinline__ void p1_proj(Frame& F, const Args& A) {
;     ...
;         for (int r = (int)blockIdx.x * NWAVES + F.wave; r < 4096 + 2 * DFF; r += F.G * NWAVES) {
;             const int sel = r >= 4096 ? 2 : (r >= 2048 ? 1 : 0); const int rr = r - 2048 * sel;
;             const bf16* src = (sel == 2 ? WSP(bf16, WS_WF1) : sel == 1 ? WSP(bf16, WS_WXKV) : WSP(bf16, WS_W1T)) + (size_t)rr * 1024; const int l = lane_now();
;             const float sc = quant_row16(*(const GAS v4u*)(src + 16 * l), *(const GAS v4u*)(src + 16 * l + 8), (sel == 2 ? WSP(unsigned char, WS_W8Q) : sel == 1 ? WSP(unsigned char, WS_WXKV8) : WSP(unsigned char, WS_W1Q)) + (size_t)rr * 1024, l);
;             if (l == 0) (sel == 2 ? WSP(float, WS_SB8Q) : sel == 1 ? WSP(float, WS_SBKV) : WSP(float, WS_SBW1))[rr] = sc;
;         }
.LBB0_555:
	s_cmp_gt_i32 s94, 1
	s_cselect_b64 s[0:1], -1, 0
	s_xor_b64 s[2:3], s[2:3], -1
	s_or_b64 s[0:1], s[0:1], s[2:3]
	s_and_b64 vcc, exec, s[0:1]
	s_cbranch_vccnz .LBB0_862
	v_readlane_b32 s0, v254, 1
	v_readlane_b32 s1, v254, 2
	s_load_dwordx2 s[12:13], s[0:1], 0x10
	s_lshl_b32 s0, s96, 3
	s_add_i32 s10, s93, s0
	s_cmpk_gt_i32 s10, 0x25ff
	s_cbranch_scc1 .LBB0_561
	s_waitcnt vmcnt(8)
	v_mbcnt_lo_u32_b32 v0, -1, 0
	v_mbcnt_hi_u32_b32 v0, -1, v0
	s_waitcnt lgkmcnt(0)
	v_and_b32_e32 v1, 64, v0
	s_lshl_b32 s11, s33, 3
	s_mov_b32 s14, 0xd00000
	s_mov_b32 s15, 0x2900000
	v_add_u32_e32 v1, 64, v1
	v_xor_b32_e32 v2, 1, v0
	v_xor_b32_e32 v3, 2, v0
	v_xor_b32_e32 v4, 4, v0
	v_xor_b32_e32 v5, 8, v0
	v_xor_b32_e32 v6, 16, v0
	v_xor_b32_e32 v7, 32, v0
	s_mov_b32 s16, 0x42fe0000
	s_mov_b32 s17, 0xc0c0400
	s_mov_b32 s18, 0x5040100
	s_mov_b32 s19, 0x2b00000
	v_mov_b32_e32 v8, 0
	v_lshlrev_b32_e32 v9, 5, v0
	s_mov_b32 s0, s10
	s_add_i32 s0, s0, s11
	s_cmpk_gt_i32 s0, 0x25ff
	s_cbranch_scc1 .Lp1pf_done
	s_cmpk_gt_i32 s0, 0x7ff
	s_cselect_b32 s2, 0xfffff800, 0
	s_cselect_b32 s3, s14, 0x100000
	s_cmpk_gt_i32 s0, 0xfff
	s_cselect_b32 s2, 0xfffff000, s2
	s_cselect_b32 s3, 0x1300000, s3
	s_add_i32 s4, s2, s0
	s_ashr_i32 s5, s4, 31
	s_lshl_b64 s[4:5], s[4:5], 11
	s_add_u32 s6, s42, s3
	s_addc_u32 s7, s43, 0
	s_add_u32 s4, s6, s4
	s_addc_u32 s5, s7, s5
	global_load_dwordx4 v[60:63], v9, s[4:5]
	global_load_dwordx4 v[60:63], v9, s[4:5] offset:16
	s_add_i32 s0, s0, s11
	s_cmpk_gt_i32 s0, 0x25ff
	s_cbranch_scc1 .Lp1pf_done
	s_cmpk_gt_i32 s0, 0x7ff
	s_cselect_b32 s2, 0xfffff800, 0
	s_cselect_b32 s3, s14, 0x100000
	s_cmpk_gt_i32 s0, 0xfff
	s_cselect_b32 s2, 0xfffff000, s2
	s_cselect_b32 s3, 0x1300000, s3
	s_add_i32 s4, s2, s0
	s_ashr_i32 s5, s4, 31
	s_lshl_b64 s[4:5], s[4:5], 11
	s_add_u32 s6, s42, s3
	s_addc_u32 s7, s43, 0
	s_add_u32 s4, s6, s4
	s_addc_u32 s5, s7, s5
	global_load_dwordx4 v[60:63], v9, s[4:5]
	global_load_dwordx4 v[60:63], v9, s[4:5] offset:16
	s_add_i32 s0, s0, s11
	s_cmpk_gt_i32 s0, 0x25ff
	s_cbranch_scc1 .Lp1pf_done
	s_cmpk_gt_i32 s0, 0x7ff
	s_cselect_b32 s2, 0xfffff800, 0
	s_cselect_b32 s3, s14, 0x100000
	s_cmpk_gt_i32 s0, 0xfff
	s_cselect_b32 s2, 0xfffff000, s2
	s_cselect_b32 s3, 0x1300000, s3
	s_add_i32 s4, s2, s0
	s_ashr_i32 s5, s4, 31
	s_lshl_b64 s[4:5], s[4:5], 11
	s_add_u32 s6, s42, s3
	s_addc_u32 s7, s43, 0
	s_add_u32 s4, s6, s4
	s_addc_u32 s5, s7, s5
	global_load_dwordx4 v[60:63], v9, s[4:5]
	global_load_dwordx4 v[60:63], v9, s[4:5] offset:16
	s_add_i32 s0, s0, s11
	s_cmpk_gt_i32 s0, 0x25ff
	s_cbranch_scc1 .Lp1pf_done
	s_cmpk_gt_i32 s0, 0x7ff
	s_cselect_b32 s2, 0xfffff800, 0
	s_cselect_b32 s3, s14, 0x100000
	s_cmpk_gt_i32 s0, 0xfff
	s_cselect_b32 s2, 0xfffff000, s2
	s_cselect_b32 s3, 0x1300000, s3
	s_add_i32 s4, s2, s0
	s_ashr_i32 s5, s4, 31
	s_lshl_b64 s[4:5], s[4:5], 11
	s_add_u32 s6, s42, s3
	s_addc_u32 s7, s43, 0
	s_add_u32 s4, s6, s4
	s_addc_u32 s5, s7, s5
	global_load_dwordx4 v[60:63], v9, s[4:5]
	global_load_dwordx4 v[60:63], v9, s[4:5] offset:16
.Lp1pf_done:
	s_branch .LBB0_559
.LBB0_558:
	s_or_b64 exec, exec, s[0:1]
	s_add_i32 s10, s10, s11
	s_cmpk_gt_i32 s10, 0x25ff
	s_cbranch_scc1 .LBB0_561
